# v038 + nt (streaming) hint on EpiC ACT stores and P1 EpiB stores
# baseline (speedup 1.0000x reference)
; __device__ __forceinline__ unsigned cvt_pk_bf16(float lo, float hi) { unsigned r; asm("v_cvt_pk_bf16_f32 %0, %1, %2" : "=v"(r) : "v"(lo), "v"(hi)); return r; }
;     __device__ __forceinline__ void operator()(const f32x4 (&acc)[2][2][4][2], const GU& u, int wr, int wc, int fr, int fq) const {
;     ...
;         for (int ai = 0; ai < 2; ++ai)
; #pragma unroll
;             for (int m = 0; m < 4; ++m) {
;                 const int row = r0 + ai * 128 + m * 16;
;                 const float rs = rsv[ai][m];
;                 bf16_t* rowp = u.out + (size_t)row * u.ldc + c0;
; #pragma unroll
;                 for (int bj = 0; bj < 2; ++bj) {
;                     if (bj == 1 && (u.mode & 8)) continue;
;                     f32x4 v0 = acc[ai][bj][m][0] * cs[bj][0] * rs, v1 = acc[ai][bj][m][1] * cs[bj][1] * rs;
;                     u32x4 w; w.x = cvt_pk_bf16(v0[0], v0[1]); w.y = cvt_pk_bf16(v0[2], v0[3]); w.z = cvt_pk_bf16(v1[0], v1[1]); w.w = cvt_pk_bf16(v1[2], v1[3]);
;                     *(u32x4*)(rowp + bj * 128) = w;
;                     if (bj == 0 && u.gates != nullptr && wc == 0) { float* gp = u.gates + (size_t)row * 32 + 8 * fq; *(f32x4*)gp = v0; *(f32x4*)(gp + 4) = v1; }
.LBB0_370:
	v_mul_lo_u32 v194, s19, v136
	v_mul_lo_u32 v195, s18, v137
	v_mad_u64_u32 v[192:193], s[0:1], s18, v136, 0
	s_cmp_lg_u64 s[20:21], 0
	v_add3_u32 v193, v193, v195, v194
	s_cselect_b64 s[0:1], -1, 0
	v_lshl_add_u64 v[192:193], v[192:193], 1, s[16:17]
	s_and_b64 s[4:5], s[8:9], s[0:1]
	v_lshl_add_u64 v[194:195], v[192:193], 0, v[200:201]
	v_pk_mul_f32 v[126:127], v[126:127], v[172:173]
	v_pk_mul_f32 v[124:125], v[124:125], v[170:171]
	v_pk_mul_f32 v[122:123], v[122:123], v[176:177]
	v_pk_mul_f32 v[120:121], v[120:121], v[168:169]
	v_cndmask_b32_e64 v192, 0, 1, s[4:5]
	v_pk_mul_f32 v[126:127], v[126:127], v[188:189] op_sel_hi:[1,0]
	v_pk_mul_f32 v[124:125], v[124:125], v[188:189] op_sel_hi:[1,0]
	v_pk_mul_f32 v[122:123], v[122:123], v[188:189] op_sel_hi:[1,0]
	v_pk_mul_f32 v[120:121], v[120:121], v[188:189] op_sel_hi:[1,0]
	v_cmp_ne_u32_e64 s[0:1], 1, v192
	s_andn2_b64 vcc, exec, s[4:5]
	v_lshlrev_b32_e32 v192, 2, v138
	v_cvt_pk_bf16_f32 v196, v124, v125
	v_cvt_pk_bf16_f32 v197, v126, v127
	v_cvt_pk_bf16_f32 v198, v120, v121
	v_cvt_pk_bf16_f32 v199, v122, v123
	flat_store_dwordx4 v[194:195], v[196:199] nt
	s_cbranch_vccnz .LBB0_372
	s_nop 0
	v_lshlrev_b64 v[196:197], 7, v[136:137]
	v_lshl_add_u64 v[196:197], s[20:21], 0, v[196:197]
	v_mov_b32_e32 v193, v201
	v_lshl_add_u64 v[196:197], v[196:197], 0, v[192:193]
	flat_store_dwordx4 v[196:197], v[124:127] nt
	flat_store_dwordx4 v[196:197], v[120:123] offset:16 nt
.LBB0_372:
	s_nop 1
	v_mov_b32_e32 v120, v188
	v_mov_b32_e32 v121, v188
	v_pk_mul_f32 v[118:119], v[118:119], v[180:181]
	v_mov_b32_e32 v122, v188
	v_mov_b32_e32 v123, v188
	v_pk_mul_f32 v[114:115], v[114:115], v[182:183]
	v_pk_mul_f32 v[112:113], v[112:113], v[174:175]
	v_pk_mul_f32 v[116:117], v[116:117], v[178:179]
	v_pk_mul_f32 v[118:119], v[118:119], v[122:123]
	v_pk_mul_f32 v[122:123], v[114:115], v[122:123]
	v_pk_mul_f32 v[114:115], v[112:113], v[120:121]
	v_pk_mul_f32 v[116:117], v[116:117], v[120:121]
	v_cvt_pk_bf16_f32 v113, v118, v119
	v_cvt_pk_bf16_f32 v114, v114, v115
	v_cvt_pk_bf16_f32 v115, v122, v123
	v_pk_mul_f32 v[110:111], v[110:111], v[172:173]
	v_cvt_pk_bf16_f32 v112, v116, v117
	flat_store_dwordx4 v[194:195], v[112:115] offset:256 nt
	v_pk_mul_f32 v[108:109], v[108:109], v[170:171]
	v_pk_mul_f32 v[106:107], v[106:107], v[176:177]
	v_mul_lo_u32 v114, s19, v142
	v_mul_lo_u32 v115, s18, v143
	v_mad_u64_u32 v[112:113], s[4:5], s18, v142, 0
	v_add3_u32 v113, v113, v115, v114
	v_lshl_add_u64 v[112:113], v[112:113], 1, s[16:17]
	v_pk_mul_f32 v[104:105], v[104:105], v[168:169]
	v_lshl_add_u64 v[112:113], v[112:113], 0, v[200:201]
	v_pk_mul_f32 v[110:111], v[110:111], v[188:189] op_sel:[0,1]
	v_pk_mul_f32 v[108:109], v[108:109], v[188:189] op_sel:[0,1]
	v_pk_mul_f32 v[106:107], v[106:107], v[188:189] op_sel:[0,1]
	v_pk_mul_f32 v[104:105], v[104:105], v[188:189] op_sel:[0,1]
	s_and_b64 vcc, exec, s[0:1]
	v_cvt_pk_bf16_f32 v114, v108, v109
	v_cvt_pk_bf16_f32 v115, v110, v111
	v_cvt_pk_bf16_f32 v116, v104, v105
	v_cvt_pk_bf16_f32 v117, v106, v107
	flat_store_dwordx4 v[112:113], v[114:117] nt
	s_cbranch_vccnz .LBB0_374
	s_nop 0
	v_lshlrev_b64 v[114:115], 7, v[142:143]
	v_lshl_add_u64 v[114:115], s[20:21], 0, v[114:115]
	v_mov_b32_e32 v193, v201
	v_lshl_add_u64 v[114:115], v[114:115], 0, v[192:193]
	flat_store_dwordx4 v[114:115], v[108:111] nt
	flat_store_dwordx4 v[114:115], v[104:107] offset:16 nt
.LBB0_374:
	v_mov_b32_e32 v188, v189
	v_pk_mul_f32 v[102:103], v[102:103], v[180:181]
	v_mov_b32_e32 v104, v189
	v_mov_b32_e32 v105, v189
	v_pk_mul_f32 v[98:99], v[98:99], v[182:183]
	v_pk_mul_f32 v[96:97], v[96:97], v[174:175]
	v_pk_mul_f32 v[100:101], v[100:101], v[178:179]
	v_pk_mul_f32 v[102:103], v[102:103], v[104:105]
	v_pk_mul_f32 v[104:105], v[98:99], v[104:105]
	v_pk_mul_f32 v[98:99], v[96:97], v[188:189]
	v_pk_mul_f32 v[100:101], v[100:101], v[188:189]
	v_cvt_pk_bf16_f32 v97, v102, v103
	v_cvt_pk_bf16_f32 v98, v98, v99
	v_cvt_pk_bf16_f32 v99, v104, v105
	v_pk_mul_f32 v[94:95], v[94:95], v[172:173]
	v_cvt_pk_bf16_f32 v96, v100, v101
	flat_store_dwordx4 v[112:113], v[96:99] offset:256 nt
	v_pk_mul_f32 v[92:93], v[92:93], v[170:171]
	v_pk_mul_f32 v[90:91], v[90:91], v[176:177]
	v_mul_lo_u32 v98, s19, v144
	v_mul_lo_u32 v99, s18, v145
	v_mad_u64_u32 v[96:97], s[4:5], s18, v144, 0
	v_add3_u32 v97, v97, v99, v98
	v_lshl_add_u64 v[96:97], v[96:97], 1, s[16:17]
	v_pk_mul_f32 v[88:89], v[88:89], v[168:169]
	v_lshl_add_u64 v[96:97], v[96:97], 0, v[200:201]
	v_pk_mul_f32 v[94:95], v[94:95], v[186:187] op_sel_hi:[1,0]
	v_pk_mul_f32 v[92:93], v[92:93], v[186:187] op_sel_hi:[1,0]
	v_pk_mul_f32 v[90:91], v[90:91], v[186:187] op_sel_hi:[1,0]
	v_pk_mul_f32 v[88:89], v[88:89], v[186:187] op_sel_hi:[1,0]
	s_and_b64 vcc, exec, s[0:1]
	v_cvt_pk_bf16_f32 v98, v92, v93
	v_cvt_pk_bf16_f32 v99, v94, v95
	v_cvt_pk_bf16_f32 v100, v88, v89
	v_cvt_pk_bf16_f32 v101, v90, v91
	flat_store_dwordx4 v[96:97], v[98:101] nt
	s_cbranch_vccnz .LBB0_376
	s_nop 0
	v_lshlrev_b64 v[98:99], 7, v[144:145]
	v_lshl_add_u64 v[98:99], s[20:21], 0, v[98:99]
	v_mov_b32_e32 v193, v201
	v_lshl_add_u64 v[98:99], v[98:99], 0, v[192:193]
	flat_store_dwordx4 v[98:99], v[92:95] nt
	flat_store_dwordx4 v[98:99], v[88:91] offset:16 nt
; __device__ __forceinline__ unsigned cvt_pk_bf16(float lo, float hi) { unsigned r; asm("v_cvt_pk_bf16_f32 %0, %1, %2" : "=v"(r) : "v"(lo), "v"(hi)); return r; }
;     __device__ __forceinline__ void operator()(const f32x4 (&acc)[2][2][4][2], const GU& u, int wr, int wc, int fr, int fq) const {
;     ...
; #pragma unroll
;         for (int ai = 0; ai < 2; ++ai)
; #pragma unroll
;             for (int m = 0; m < 4; ++m) {
;                 const int row = r0 + ai * 128 + m * 16;
;                 const float rs = rsv[ai][m];
;                 bf16_t* rowp = u.out + (size_t)row * u.ldc + c0;
; #pragma unroll
;                 for (int bj = 0; bj < 2; ++bj) {
;                     if (bj == 1 && (u.mode & 8)) continue;
;                     f32x4 v0 = acc[ai][bj][m][0] * cs[bj][0] * rs, v1 = acc[ai][bj][m][1] * cs[bj][1] * rs;
;                     u32x4 w; w.x = cvt_pk_bf16(v0[0], v0[1]); w.y = cvt_pk_bf16(v0[2], v0[3]); w.z = cvt_pk_bf16(v1[0], v1[1]); w.w = cvt_pk_bf16(v1[2], v1[3]);
;                     *(u32x4*)(rowp + bj * 128) = w;
;                     if (bj == 0 && u.gates != nullptr && wc == 0) { float* gp = u.gates + (size_t)row * 32 + 8 * fq; *(f32x4*)gp = v0; *(f32x4*)(gp + 4) = v1; }
;                 }
.LBB0_376:
	s_nop 1
	v_mov_b32_e32 v88, v186
	v_mov_b32_e32 v89, v186
	v_pk_mul_f32 v[86:87], v[86:87], v[180:181]
	v_mov_b32_e32 v90, v186
	v_mov_b32_e32 v91, v186
	v_pk_mul_f32 v[82:83], v[82:83], v[182:183]
	v_pk_mul_f32 v[80:81], v[80:81], v[174:175]
	v_pk_mul_f32 v[84:85], v[84:85], v[178:179]
	v_pk_mul_f32 v[86:87], v[86:87], v[90:91]
	v_pk_mul_f32 v[90:91], v[82:83], v[90:91]
	v_pk_mul_f32 v[82:83], v[80:81], v[88:89]
	v_pk_mul_f32 v[84:85], v[84:85], v[88:89]
	v_cvt_pk_bf16_f32 v81, v86, v87
	v_cvt_pk_bf16_f32 v82, v82, v83
	v_cvt_pk_bf16_f32 v83, v90, v91
	v_pk_mul_f32 v[78:79], v[78:79], v[172:173]
	v_cvt_pk_bf16_f32 v80, v84, v85
	flat_store_dwordx4 v[96:97], v[80:83] offset:256 nt
	v_pk_mul_f32 v[76:77], v[76:77], v[170:171]
	v_pk_mul_f32 v[74:75], v[74:75], v[176:177]
	v_mul_lo_u32 v82, s19, v146
	v_mul_lo_u32 v83, s18, v147
	v_mad_u64_u32 v[80:81], s[4:5], s18, v146, 0
	v_add3_u32 v81, v81, v83, v82
	v_lshl_add_u64 v[80:81], v[80:81], 1, s[16:17]
	v_pk_mul_f32 v[72:73], v[72:73], v[168:169]
	v_lshl_add_u64 v[80:81], v[80:81], 0, v[200:201]
	v_pk_mul_f32 v[78:79], v[78:79], v[186:187] op_sel:[0,1]
	v_pk_mul_f32 v[76:77], v[76:77], v[186:187] op_sel:[0,1]
	v_pk_mul_f32 v[74:75], v[74:75], v[186:187] op_sel:[0,1]
	v_pk_mul_f32 v[72:73], v[72:73], v[186:187] op_sel:[0,1]
	s_and_b64 vcc, exec, s[0:1]
	v_cvt_pk_bf16_f32 v82, v76, v77
	v_cvt_pk_bf16_f32 v83, v78, v79
	v_cvt_pk_bf16_f32 v84, v72, v73
	v_cvt_pk_bf16_f32 v85, v74, v75
	flat_store_dwordx4 v[80:81], v[82:85] nt
	s_cbranch_vccnz .LBB0_378
	s_nop 0
	v_lshlrev_b64 v[82:83], 7, v[146:147]
	v_lshl_add_u64 v[82:83], s[20:21], 0, v[82:83]
	v_mov_b32_e32 v193, v201
	v_lshl_add_u64 v[82:83], v[82:83], 0, v[192:193]
	flat_store_dwordx4 v[82:83], v[76:79] nt
	flat_store_dwordx4 v[82:83], v[72:75] offset:16 nt
.LBB0_378:
	v_mov_b32_e32 v186, v187
	v_pk_mul_f32 v[70:71], v[70:71], v[180:181]
	v_mov_b32_e32 v72, v187
	v_mov_b32_e32 v73, v187
	v_pk_mul_f32 v[66:67], v[66:67], v[182:183]
	v_pk_mul_f32 v[64:65], v[64:65], v[174:175]
	v_pk_mul_f32 v[68:69], v[68:69], v[178:179]
	v_pk_mul_f32 v[70:71], v[70:71], v[72:73]
	v_pk_mul_f32 v[72:73], v[66:67], v[72:73]
	v_pk_mul_f32 v[66:67], v[64:65], v[186:187]
	v_pk_mul_f32 v[68:69], v[68:69], v[186:187]
	v_cvt_pk_bf16_f32 v65, v70, v71
	v_cvt_pk_bf16_f32 v66, v66, v67
	v_cvt_pk_bf16_f32 v67, v72, v73
	v_pk_mul_f32 v[62:63], v[62:63], v[172:173]
	v_cvt_pk_bf16_f32 v64, v68, v69
	flat_store_dwordx4 v[80:81], v[64:67] offset:256 nt
	v_pk_mul_f32 v[60:61], v[60:61], v[170:171]
	v_pk_mul_f32 v[58:59], v[58:59], v[176:177]
	v_mul_lo_u32 v66, s19, v148
	v_mul_lo_u32 v67, s18, v149
	v_mad_u64_u32 v[64:65], s[4:5], s18, v148, 0
	v_add3_u32 v65, v65, v67, v66
	v_lshl_add_u64 v[64:65], v[64:65], 1, s[16:17]
	v_pk_mul_f32 v[56:57], v[56:57], v[168:169]
	v_lshl_add_u64 v[64:65], v[64:65], 0, v[200:201]
	v_pk_mul_f32 v[62:63], v[62:63], v[184:185] op_sel_hi:[1,0]
	v_pk_mul_f32 v[60:61], v[60:61], v[184:185] op_sel_hi:[1,0]
	v_pk_mul_f32 v[58:59], v[58:59], v[184:185] op_sel_hi:[1,0]
	v_pk_mul_f32 v[56:57], v[56:57], v[184:185] op_sel_hi:[1,0]
	s_and_b64 vcc, exec, s[0:1]
	v_cvt_pk_bf16_f32 v66, v60, v61
	v_cvt_pk_bf16_f32 v67, v62, v63
	v_cvt_pk_bf16_f32 v68, v56, v57
	v_cvt_pk_bf16_f32 v69, v58, v59
	flat_store_dwordx4 v[64:65], v[66:69] nt
	s_cbranch_vccnz .LBB0_380
	s_nop 0
	v_lshl_add_u64 v[66:67], s[20:21], 0, v[150:151]
	v_mov_b32_e32 v193, v201
	v_lshl_add_u64 v[66:67], v[66:67], 0, v[192:193]
	flat_store_dwordx4 v[66:67], v[60:63] nt
	flat_store_dwordx4 v[66:67], v[56:59] offset:16 nt
.LBB0_380:
	s_nop 1
	v_mov_b32_e32 v56, v184
	v_mov_b32_e32 v57, v184
	v_pk_mul_f32 v[54:55], v[54:55], v[180:181]
	v_mov_b32_e32 v58, v184
	v_mov_b32_e32 v59, v184
	v_pk_mul_f32 v[50:51], v[50:51], v[182:183]
	v_pk_mul_f32 v[48:49], v[48:49], v[174:175]
	v_pk_mul_f32 v[52:53], v[52:53], v[178:179]
	v_pk_mul_f32 v[54:55], v[54:55], v[58:59]
	v_pk_mul_f32 v[58:59], v[50:51], v[58:59]
	v_pk_mul_f32 v[50:51], v[48:49], v[56:57]
	v_pk_mul_f32 v[52:53], v[52:53], v[56:57]
	v_cvt_pk_bf16_f32 v49, v54, v55
	v_cvt_pk_bf16_f32 v50, v50, v51
	v_cvt_pk_bf16_f32 v51, v58, v59
	v_pk_mul_f32 v[46:47], v[46:47], v[172:173]
	v_cvt_pk_bf16_f32 v48, v52, v53
	flat_store_dwordx4 v[64:65], v[48:51] offset:256 nt
	v_pk_mul_f32 v[44:45], v[44:45], v[170:171]
	v_pk_mul_f32 v[42:43], v[42:43], v[176:177]
	v_mul_lo_u32 v50, s19, v152
	v_mul_lo_u32 v51, s18, v153
	v_mad_u64_u32 v[48:49], s[4:5], s18, v152, 0
	v_add3_u32 v49, v49, v51, v50
	v_lshl_add_u64 v[48:49], v[48:49], 1, s[16:17]
	v_pk_mul_f32 v[40:41], v[40:41], v[168:169]
	v_lshl_add_u64 v[48:49], v[48:49], 0, v[200:201]
	v_pk_mul_f32 v[46:47], v[46:47], v[184:185] op_sel:[0,1]
	v_pk_mul_f32 v[44:45], v[44:45], v[184:185] op_sel:[0,1]
	v_pk_mul_f32 v[42:43], v[42:43], v[184:185] op_sel:[0,1]
	v_pk_mul_f32 v[40:41], v[40:41], v[184:185] op_sel:[0,1]
	s_and_b64 vcc, exec, s[0:1]
	v_cvt_pk_bf16_f32 v50, v44, v45
	v_cvt_pk_bf16_f32 v51, v46, v47
	v_cvt_pk_bf16_f32 v52, v40, v41
	v_cvt_pk_bf16_f32 v53, v42, v43
	flat_store_dwordx4 v[48:49], v[50:53] nt
	s_cbranch_vccnz .LBB0_382
	s_nop 0
	v_lshl_add_u64 v[50:51], s[20:21], 0, v[154:155]
	v_mov_b32_e32 v193, v201
	v_lshl_add_u64 v[50:51], v[50:51], 0, v[192:193]
	flat_store_dwordx4 v[50:51], v[44:47] nt
	flat_store_dwordx4 v[50:51], v[40:43] offset:16 nt
; __device__ __forceinline__ unsigned cvt_pk_bf16(float lo, float hi) { unsigned r; asm("v_cvt_pk_bf16_f32 %0, %1, %2" : "=v"(r) : "v"(lo), "v"(hi)); return r; }
; #define PG8_BAR __builtin_amdgcn_s_barrier()
;     __device__ __forceinline__ CU2 full(int i) const { const int Lx = i * G + c; CU2 u; tile_order(Lx, 33, 44, u.pm, u.pn); return u; }
; template <class Epi, class Sched, bool APERM = false, bool HALFN = false>
; __device__ __forceinline__ void gemm_phase(LAS unsigned char* lds, const int tid_in, const int K, const Sched& S, const Epi& E) {
;     ...
;         if (wr == 0) PG8_BAR;
;         { const Unit fu = S.full(ui); E(acc, fu, wr, wc, fr, fq); }
;         if (!has_next) break;
; #pragma unroll
;         for (int a = 0; a < 2; ++a)
; #pragma unroll
;             for (int b = 0; b < 2; ++b)
; #pragma unroll
;                 for (int m = 0; m < 4; ++m)
; #pragma unroll
;                     for (int n = 0; n < 2; ++n) acc[a][b][m][n] = (f32x4){0.f, 0.f, 0.f, 0.f};
;         cur = nxt; cA = nA; cB = nB; ++ui;
;         if (wr == 1) PG8_BAR;
;     __device__ __forceinline__ void operator()(const f32x4 (&acc)[2][2][4][2], const GU& u, int wr, int wc, int fr, int fq) const {
;     ...
; #pragma unroll
;         for (int ai = 0; ai < 2; ++ai)
; #pragma unroll
;             for (int m = 0; m < 4; ++m) {
;                 const int row = r0 + ai * 128 + m * 16;
;                 const float rs = rsv[ai][m];
;                 bf16_t* rowp = u.out + (size_t)row * u.ldc + c0;
; #pragma unroll
;                 for (int bj = 0; bj < 2; ++bj) {
;                     if (bj == 1 && (u.mode & 8)) continue;
;                     f32x4 v0 = acc[ai][bj][m][0] * cs[bj][0] * rs, v1 = acc[ai][bj][m][1] * cs[bj][1] * rs;
;                     u32x4 w; w.x = cvt_pk_bf16(v0[0], v0[1]); w.y = cvt_pk_bf16(v0[2], v0[3]); w.z = cvt_pk_bf16(v1[0], v1[1]); w.w = cvt_pk_bf16(v1[2], v1[3]);
;                     *(u32x4*)(rowp + bj * 128) = w;
;                     if (bj == 0 && u.gates != nullptr && wc == 0) { float* gp = u.gates + (size_t)row * 32 + 8 * fq; *(f32x4*)gp = v0; *(f32x4*)(gp + 4) = v1; }
;                 }
.LBB0_382:
	v_mov_b32_e32 v184, v185
	v_pk_mul_f32 v[38:39], v[38:39], v[180:181]
	v_mov_b32_e32 v40, v185
	v_mov_b32_e32 v41, v185
	v_pk_mul_f32 v[34:35], v[34:35], v[182:183]
	v_pk_mul_f32 v[32:33], v[32:33], v[174:175]
	v_pk_mul_f32 v[36:37], v[36:37], v[178:179]
	v_pk_mul_f32 v[38:39], v[38:39], v[40:41]
	v_pk_mul_f32 v[40:41], v[34:35], v[40:41]
	v_pk_mul_f32 v[34:35], v[32:33], v[184:185]
	v_pk_mul_f32 v[36:37], v[36:37], v[184:185]
	v_cvt_pk_bf16_f32 v33, v38, v39
	v_cvt_pk_bf16_f32 v34, v34, v35
	v_cvt_pk_bf16_f32 v35, v40, v41
	v_pk_mul_f32 v[30:31], v[30:31], v[172:173]
	v_cvt_pk_bf16_f32 v32, v36, v37
	flat_store_dwordx4 v[48:49], v[32:35] offset:256 nt
	v_pk_mul_f32 v[28:29], v[28:29], v[170:171]
	v_pk_mul_f32 v[26:27], v[26:27], v[176:177]
	v_mul_lo_u32 v34, s19, v156
	v_mul_lo_u32 v35, s18, v157
	v_mad_u64_u32 v[32:33], s[4:5], s18, v156, 0
	v_add3_u32 v33, v33, v35, v34
	v_lshl_add_u64 v[32:33], v[32:33], 1, s[16:17]
	v_pk_mul_f32 v[24:25], v[24:25], v[168:169]
	v_lshl_add_u64 v[32:33], v[32:33], 0, v[200:201]
	v_pk_mul_f32 v[30:31], v[30:31], v[190:191] op_sel_hi:[1,0]
	v_pk_mul_f32 v[28:29], v[28:29], v[190:191] op_sel_hi:[1,0]
	v_pk_mul_f32 v[26:27], v[26:27], v[190:191] op_sel_hi:[1,0]
	v_pk_mul_f32 v[24:25], v[24:25], v[190:191] op_sel_hi:[1,0]
	s_and_b64 vcc, exec, s[0:1]
	v_cvt_pk_bf16_f32 v34, v28, v29
	v_cvt_pk_bf16_f32 v35, v30, v31
	v_cvt_pk_bf16_f32 v36, v24, v25
	v_cvt_pk_bf16_f32 v37, v26, v27
	flat_store_dwordx4 v[32:33], v[34:37] nt
	s_cbranch_vccnz .LBB0_384
	s_nop 0
	v_lshl_add_u64 v[34:35], s[20:21], 0, v[158:159]
	v_mov_b32_e32 v193, v201
	v_lshl_add_u64 v[34:35], v[34:35], 0, v[192:193]
	flat_store_dwordx4 v[34:35], v[28:31] nt
	flat_store_dwordx4 v[34:35], v[24:27] offset:16 nt
.LBB0_384:
	s_nop 1
	v_mov_b32_e32 v24, v190
	v_mov_b32_e32 v25, v190
	v_pk_mul_f32 v[22:23], v[22:23], v[180:181]
	v_mov_b32_e32 v26, v190
	v_mov_b32_e32 v27, v190
	v_pk_mul_f32 v[18:19], v[18:19], v[182:183]
	v_pk_mul_f32 v[16:17], v[16:17], v[174:175]
	v_pk_mul_f32 v[20:21], v[20:21], v[178:179]
	v_pk_mul_f32 v[22:23], v[22:23], v[26:27]
	v_pk_mul_f32 v[26:27], v[18:19], v[26:27]
	v_pk_mul_f32 v[18:19], v[16:17], v[24:25]
	v_pk_mul_f32 v[20:21], v[20:21], v[24:25]
	v_cvt_pk_bf16_f32 v17, v22, v23
	v_cvt_pk_bf16_f32 v18, v18, v19
	v_cvt_pk_bf16_f32 v19, v26, v27
	v_pk_mul_f32 v[14:15], v[14:15], v[172:173]
	v_cvt_pk_bf16_f32 v16, v20, v21
	flat_store_dwordx4 v[32:33], v[16:19] offset:256 nt
	v_pk_mul_f32 v[12:13], v[12:13], v[170:171]
	v_pk_mul_f32 v[10:11], v[10:11], v[176:177]
	v_mul_lo_u32 v18, s19, v160
	v_mul_lo_u32 v19, s18, v161
	v_mad_u64_u32 v[16:17], s[4:5], s18, v160, 0
	v_add3_u32 v17, v17, v19, v18
	v_lshl_add_u64 v[16:17], v[16:17], 1, s[16:17]
	v_pk_mul_f32 v[8:9], v[8:9], v[168:169]
	v_lshl_add_u64 v[16:17], v[16:17], 0, v[200:201]
	v_pk_mul_f32 v[14:15], v[14:15], v[190:191] op_sel:[0,1]
	v_pk_mul_f32 v[12:13], v[12:13], v[190:191] op_sel:[0,1]
	v_pk_mul_f32 v[10:11], v[10:11], v[190:191] op_sel:[0,1]
	v_pk_mul_f32 v[8:9], v[8:9], v[190:191] op_sel:[0,1]
	s_and_b64 vcc, exec, s[0:1]
	v_cvt_pk_bf16_f32 v18, v12, v13
	v_cvt_pk_bf16_f32 v19, v14, v15
	v_cvt_pk_bf16_f32 v20, v8, v9
	v_cvt_pk_bf16_f32 v21, v10, v11
	flat_store_dwordx4 v[16:17], v[18:21] nt
	s_cbranch_vccnz .LBB0_386
	s_nop 0
	v_lshl_add_u64 v[18:19], s[20:21], 0, v[162:163]
	v_mov_b32_e32 v193, v201
	v_lshl_add_u64 v[18:19], v[18:19], 0, v[192:193]
	flat_store_dwordx4 v[18:19], v[12:15] nt
	flat_store_dwordx4 v[18:19], v[8:11] offset:16 nt
.LBB0_386:
	v_mov_b32_e32 v190, v191
	v_pk_mul_f32 v[6:7], v[6:7], v[180:181]
	v_mov_b32_e32 v8, v191
	v_mov_b32_e32 v9, v191
	v_pk_mul_f32 v[2:3], v[2:3], v[182:183]
	v_pk_mul_f32 v[0:1], v[0:1], v[174:175]
	v_pk_mul_f32 v[4:5], v[4:5], v[178:179]
	v_pk_mul_f32 v[6:7], v[6:7], v[8:9]
	v_pk_mul_f32 v[8:9], v[2:3], v[8:9]
	v_pk_mul_f32 v[2:3], v[0:1], v[190:191]
	s_andn2_b64 vcc, exec, s[14:15]
	s_mov_b64 s[0:1], -1
	v_readlane_b32 s19, v255, 1
	v_pk_mul_f32 v[4:5], v[4:5], v[190:191]
	v_cvt_pk_bf16_f32 v1, v6, v7
	v_cvt_pk_bf16_f32 v2, v2, v3
	v_cvt_pk_bf16_f32 v3, v8, v9
	s_nop 0
	v_cvt_pk_bf16_f32 v0, v4, v5
	flat_store_dwordx4 v[16:17], v[0:3] offset:256 nt
	s_cbranch_vccnz .LBB0_335
	s_andn2_b64 vcc, exec, s[2:3]
	s_cbranch_vccnz .LBB0_334
	s_barrier
	s_branch .LBB0_334

; __device__ __forceinline__ unsigned cvt_pk_bf16(float lo, float hi) { unsigned r; asm("v_cvt_pk_bf16_f32 %0, %1, %2" : "=v"(r) : "v"(lo), "v"(hi)); return r; }
;     __device__ __forceinline__ void operator()(const f32x4 (&acc)[2][2][4][2], const CU2& u, int wr, int wc, int fr_, int fq_) const {
;     ...
;             for (int j = 0; j < 8; ++j) {
;                 const f32x4 xg = acc[j >> 2][0][j & 3][n] * rsv[j], xv = acc[j >> 2][1][j & 3][n] * rsv[j];
;                 const f32x4 gc = gb + g2 * xg + g1 * pg1 + g0 * pg2, vc = vb + v2 * xv + v1 * pv1 + v0 * pv2;
;                 f32x4 sg;
; #pragma unroll
;                 for (int e = 0; e < 4; ++e) sg[e] = __builtin_amdgcn_rcpf(1.f + __expf(-gc[e]));
;                 const f32x4 o4 = gc * sg * vc;
;                 pg2 = pg1; pg1 = xg; pv2 = pv1; pv1 = xv;
;                 if (rb + j >= 2 && tb + j < T_) { u32x2 w; w.x = cvt_pk_bf16(o4[0], o4[1]); w.y = cvt_pk_bf16(o4[2], o4[3]); *(u32x2*)(act + (size_t)(tb + j) * FF_ + 128 * u.pn + cl + 4 * n) = w; }
.LBB0_949:
	s_or_b64 exec, exec, s[30:31]
	v_mov_b32_e32 v229, v228
	v_mov_b32_e32 v114, v228
	v_mov_b32_e32 v115, v228
	v_pk_mul_f32 v[60:61], v[60:61], v[114:115]
	v_pk_mul_f32 v[58:59], v[58:59], v[228:229]
	v_pk_mul_f32 v[42:43], v[42:43], v[114:115]
	v_pk_mul_f32 v[40:41], v[40:41], v[228:229]
	s_and_saveexec_b64 s[4:5], s[10:11]
	s_cbranch_execz .LBB0_951
	s_waitcnt lgkmcnt(0)
	v_pk_fma_f32 v[114:115], v[42:43], v[102:103], v[106:107]
	v_pk_fma_f32 v[116:117], v[40:41], v[100:101], v[104:105]
	s_waitcnt lgkmcnt(0)
	v_pk_fma_f32 v[114:115], v[98:99], v[56:57], v[114:115]
	v_pk_fma_f32 v[116:117], v[96:97], v[54:55], v[116:117]
	v_pk_fma_f32 v[74:75], v[82:83], v[74:75], v[114:115]
	v_pk_fma_f32 v[72:73], v[80:81], v[72:73], v[116:117]
	v_pk_fma_f32 v[114:115], v[60:61], v[90:91], v[94:95]
	v_pk_fma_f32 v[116:117], v[58:59], v[88:89], v[92:93]
	v_pk_fma_f32 v[114:115], v[86:87], v[46:47], v[114:115]
	v_pk_fma_f32 v[116:117], v[84:85], v[44:45], v[116:117]
	v_pk_fma_f32 v[70:71], v[78:79], v[70:71], v[114:115]
	v_pk_fma_f32 v[68:69], v[76:77], v[68:69], v[116:117]
	v_mul_f32_e32 v116, 0xbfb8aa3b, v70
	v_mul_f32_e32 v114, 0xbfb8aa3b, v68
	v_mul_f32_e32 v115, 0xbfb8aa3b, v69
	v_mul_f32_e32 v117, 0xbfb8aa3b, v71
	v_exp_f32_e32 v114, v114
	v_exp_f32_e32 v115, v115
	v_exp_f32_e32 v116, v116
	v_exp_f32_e32 v117, v117
	v_add_f32_e32 v114, 1.0, v114
	v_add_f32_e32 v115, 1.0, v115
	v_add_f32_e32 v116, 1.0, v116
	v_add_f32_e32 v117, 1.0, v117
	v_rcp_f32_e32 v114, v114
	v_rcp_f32_e32 v115, v115
	v_rcp_f32_e32 v116, v116
	v_rcp_f32_e32 v117, v117
	v_pk_mul_f32 v[68:69], v[68:69], v[114:115]
	s_nop 0
	v_pk_mul_f32 v[68:69], v[72:73], v[68:69]
	v_pk_mul_f32 v[70:71], v[70:71], v[116:117]
	v_cvt_pk_bf16_f32 v150, v68, v69
	s_nop 0
	v_pk_mul_f32 v[70:71], v[74:75], v[70:71]
	s_nop 0
	v_cvt_pk_bf16_f32 v151, v70, v71
	v_mad_i64_i32 v[70:71], s[10:11], v200, s37, v[50:51]
	global_store_dwordx4 v[70:71], v[148:151], off nt
.LBB0_951:
	s_or_b64 exec, exec, s[4:5]
	v_mov_b32_e32 v225, v224
	s_waitcnt lgkmcnt(0)
	v_mov_b32_e32 v68, v224
	v_mov_b32_e32 v69, v224
	v_pk_mul_f32 v[38:39], v[38:39], v[68:69]
	v_pk_mul_f32 v[36:37], v[36:37], v[224:225]
	v_pk_mul_f32 v[34:35], v[34:35], v[68:69]
	v_pk_mul_f32 v[32:33], v[32:33], v[224:225]
	s_and_saveexec_b64 s[4:5], s[6:7]
	s_cbranch_execz .LBB0_953
	v_pk_fma_f32 v[68:69], v[34:35], v[102:103], v[106:107]
	v_pk_fma_f32 v[70:71], v[32:33], v[100:101], v[104:105]
	v_pk_fma_f32 v[68:69], v[42:43], v[98:99], v[68:69]
	v_pk_fma_f32 v[70:71], v[40:41], v[96:97], v[70:71]
	v_pk_fma_f32 v[56:57], v[82:83], v[56:57], v[68:69]
	v_pk_fma_f32 v[54:55], v[80:81], v[54:55], v[70:71]
	v_pk_fma_f32 v[68:69], v[38:39], v[90:91], v[94:95]
	v_pk_fma_f32 v[70:71], v[36:37], v[88:89], v[92:93]
	v_pk_fma_f32 v[68:69], v[60:61], v[86:87], v[68:69]
	v_pk_fma_f32 v[70:71], v[58:59], v[84:85], v[70:71]
	v_pk_fma_f32 v[46:47], v[78:79], v[46:47], v[68:69]
	v_pk_fma_f32 v[44:45], v[76:77], v[44:45], v[70:71]
	v_mul_f32_e32 v70, 0xbfb8aa3b, v46
	v_mul_f32_e32 v68, 0xbfb8aa3b, v44
	v_mul_f32_e32 v69, 0xbfb8aa3b, v45
	v_mul_f32_e32 v71, 0xbfb8aa3b, v47
	v_exp_f32_e32 v68, v68
	v_exp_f32_e32 v69, v69
	v_exp_f32_e32 v70, v70
	v_exp_f32_e32 v71, v71
	v_add_f32_e32 v68, 1.0, v68
	v_add_f32_e32 v69, 1.0, v69
	v_add_f32_e32 v70, 1.0, v70
	v_add_f32_e32 v71, 1.0, v71
	v_rcp_f32_e32 v68, v68
	v_rcp_f32_e32 v69, v69
	v_rcp_f32_e32 v70, v70
	v_rcp_f32_e32 v71, v71
	v_pk_mul_f32 v[44:45], v[44:45], v[68:69]
	s_nop 0
	v_pk_mul_f32 v[44:45], v[54:55], v[44:45]
	v_pk_mul_f32 v[46:47], v[46:47], v[70:71]
	v_cvt_pk_bf16_f32 v146, v44, v45
	s_nop 0
	v_pk_mul_f32 v[46:47], v[56:57], v[46:47]
	s_nop 0
	v_cvt_pk_bf16_f32 v147, v46, v47
	v_mad_i64_i32 v[46:47], s[6:7], v223, s37, v[50:51]
	global_store_dwordx4 v[46:47], v[144:147], off nt
.LBB0_953:
	s_or_b64 exec, exec, s[4:5]
	v_mov_b32_e32 v223, v222
	v_mov_b32_e32 v44, v222
	v_mov_b32_e32 v45, v222
	v_pk_mul_f32 v[30:31], v[30:31], v[44:45]
	v_pk_mul_f32 v[28:29], v[28:29], v[222:223]
	v_pk_mul_f32 v[26:27], v[26:27], v[44:45]
	v_pk_mul_f32 v[24:25], v[24:25], v[222:223]
	s_and_saveexec_b64 s[4:5], s[8:9]
	s_cbranch_execz .LBB0_955
	v_pk_fma_f32 v[44:45], v[26:27], v[102:103], v[106:107]
	v_pk_fma_f32 v[46:47], v[24:25], v[100:101], v[104:105]
	v_pk_fma_f32 v[44:45], v[34:35], v[98:99], v[44:45]
	v_pk_fma_f32 v[46:47], v[32:33], v[96:97], v[46:47]
	v_pk_fma_f32 v[42:43], v[42:43], v[82:83], v[44:45]
	v_pk_fma_f32 v[40:41], v[40:41], v[80:81], v[46:47]
	v_pk_fma_f32 v[44:45], v[30:31], v[90:91], v[94:95]
	v_pk_fma_f32 v[46:47], v[28:29], v[88:89], v[92:93]
	v_pk_fma_f32 v[44:45], v[38:39], v[86:87], v[44:45]
	v_pk_fma_f32 v[46:47], v[36:37], v[84:85], v[46:47]
	v_pk_fma_f32 v[44:45], v[60:61], v[78:79], v[44:45]
	v_pk_fma_f32 v[46:47], v[58:59], v[76:77], v[46:47]
	v_mul_f32_e32 v56, 0xbfb8aa3b, v44
	v_mul_f32_e32 v54, 0xbfb8aa3b, v46
	v_mul_f32_e32 v55, 0xbfb8aa3b, v47
	v_mul_f32_e32 v57, 0xbfb8aa3b, v45
	v_exp_f32_e32 v54, v54
	v_exp_f32_e32 v55, v55
	v_exp_f32_e32 v56, v56
	v_exp_f32_e32 v57, v57
	v_add_f32_e32 v54, 1.0, v54
	v_add_f32_e32 v55, 1.0, v55
	v_add_f32_e32 v56, 1.0, v56
	v_add_f32_e32 v57, 1.0, v57
	v_rcp_f32_e32 v54, v54
	v_rcp_f32_e32 v55, v55
	v_rcp_f32_e32 v56, v56
	v_rcp_f32_e32 v57, v57
	v_pk_mul_f32 v[46:47], v[46:47], v[54:55]
	s_nop 0
	v_pk_mul_f32 v[40:41], v[40:41], v[46:47]
	v_pk_mul_f32 v[44:45], v[44:45], v[56:57]
	v_cvt_pk_bf16_f32 v186, v40, v41
	s_nop 0
	v_pk_mul_f32 v[42:43], v[42:43], v[44:45]
	s_nop 0
	v_cvt_pk_bf16_f32 v187, v42, v43
	v_mad_i64_i32 v[42:43], s[6:7], v221, s37, v[50:51]
	global_store_dwordx4 v[42:43], v[184:187], off nt
; __device__ __forceinline__ unsigned cvt_pk_bf16(float lo, float hi) { unsigned r; asm("v_cvt_pk_bf16_f32 %0, %1, %2" : "=v"(r) : "v"(lo), "v"(hi)); return r; }
;     __device__ __forceinline__ void operator()(const f32x4 (&acc)[2][2][4][2], const CU2& u, int wr, int wc, int fr_, int fq_) const {
;     ...
;             for (int j = 0; j < 8; ++j) {
;                 const f32x4 xg = acc[j >> 2][0][j & 3][n] * rsv[j], xv = acc[j >> 2][1][j & 3][n] * rsv[j];
;                 const f32x4 gc = gb + g2 * xg + g1 * pg1 + g0 * pg2, vc = vb + v2 * xv + v1 * pv1 + v0 * pv2;
;                 f32x4 sg;
; #pragma unroll
;                 for (int e = 0; e < 4; ++e) sg[e] = __builtin_amdgcn_rcpf(1.f + __expf(-gc[e]));
;                 const f32x4 o4 = gc * sg * vc;
;                 pg2 = pg1; pg1 = xg; pv2 = pv1; pv1 = xv;
;                 if (rb + j >= 2 && tb + j < T_) { u32x2 w; w.x = cvt_pk_bf16(o4[0], o4[1]); w.y = cvt_pk_bf16(o4[2], o4[3]); *(u32x2*)(act + (size_t)(tb + j) * FF_ + 128 * u.pn + cl + 4 * n) = w; }
.LBB0_955:
	s_or_b64 exec, exec, s[4:5]
	v_mov_b32_e32 v221, v220
	v_mov_b32_e32 v40, v220
	v_mov_b32_e32 v41, v220
	v_pk_mul_f32 v[22:23], v[22:23], v[40:41]
	v_pk_mul_f32 v[20:21], v[20:21], v[220:221]
	v_pk_mul_f32 v[18:19], v[18:19], v[40:41]
	v_pk_mul_f32 v[16:17], v[16:17], v[220:221]
	s_and_saveexec_b64 s[4:5], s[12:13]
	s_cbranch_execz .LBB0_957
	v_pk_fma_f32 v[40:41], v[18:19], v[102:103], v[106:107]
	v_pk_fma_f32 v[42:43], v[16:17], v[100:101], v[104:105]
	v_pk_fma_f32 v[40:41], v[26:27], v[98:99], v[40:41]
	v_pk_fma_f32 v[42:43], v[24:25], v[96:97], v[42:43]
	v_pk_fma_f32 v[34:35], v[34:35], v[82:83], v[40:41]
	v_pk_fma_f32 v[32:33], v[32:33], v[80:81], v[42:43]
	v_pk_fma_f32 v[40:41], v[22:23], v[90:91], v[94:95]
	v_pk_fma_f32 v[42:43], v[20:21], v[88:89], v[92:93]
	v_pk_fma_f32 v[40:41], v[30:31], v[86:87], v[40:41]
	v_pk_fma_f32 v[42:43], v[28:29], v[84:85], v[42:43]
	v_pk_fma_f32 v[38:39], v[38:39], v[78:79], v[40:41]
	v_pk_fma_f32 v[36:37], v[36:37], v[76:77], v[42:43]
	v_mul_f32_e32 v42, 0xbfb8aa3b, v38
	v_mul_f32_e32 v40, 0xbfb8aa3b, v36
	v_mul_f32_e32 v41, 0xbfb8aa3b, v37
	v_mul_f32_e32 v43, 0xbfb8aa3b, v39
	v_exp_f32_e32 v40, v40
	v_exp_f32_e32 v41, v41
	v_exp_f32_e32 v42, v42
	v_exp_f32_e32 v43, v43
	v_add_f32_e32 v40, 1.0, v40
	v_add_f32_e32 v41, 1.0, v41
	v_add_f32_e32 v42, 1.0, v42
	v_add_f32_e32 v43, 1.0, v43
	v_rcp_f32_e32 v40, v40
	v_rcp_f32_e32 v41, v41
	v_rcp_f32_e32 v42, v42
	v_rcp_f32_e32 v43, v43
	v_pk_mul_f32 v[36:37], v[36:37], v[40:41]
	s_nop 0
	v_pk_mul_f32 v[32:33], v[32:33], v[36:37]
	v_pk_mul_f32 v[38:39], v[38:39], v[42:43]
	v_cvt_pk_bf16_f32 v190, v32, v33
	s_nop 0
	v_pk_mul_f32 v[34:35], v[34:35], v[38:39]
	s_nop 0
	v_cvt_pk_bf16_f32 v191, v34, v35
	v_mad_i64_i32 v[34:35], s[6:7], v219, s37, v[50:51]
	global_store_dwordx4 v[34:35], v[188:191], off nt
.LBB0_957:
	s_or_b64 exec, exec, s[4:5]
	v_mov_b32_e32 v219, v218
	v_mov_b32_e32 v32, v218
	v_mov_b32_e32 v33, v218
	v_pk_mul_f32 v[14:15], v[14:15], v[32:33]
	v_pk_mul_f32 v[12:13], v[12:13], v[218:219]
	v_pk_mul_f32 v[10:11], v[10:11], v[32:33]
	v_pk_mul_f32 v[8:9], v[8:9], v[218:219]
	s_and_saveexec_b64 s[4:5], s[14:15]
	s_cbranch_execz .LBB0_959
	v_pk_fma_f32 v[32:33], v[10:11], v[102:103], v[106:107]
	v_pk_fma_f32 v[34:35], v[8:9], v[100:101], v[104:105]
	v_pk_fma_f32 v[32:33], v[18:19], v[98:99], v[32:33]
	v_pk_fma_f32 v[34:35], v[16:17], v[96:97], v[34:35]
	v_pk_fma_f32 v[26:27], v[26:27], v[82:83], v[32:33]
	v_pk_fma_f32 v[24:25], v[24:25], v[80:81], v[34:35]
	v_pk_fma_f32 v[32:33], v[14:15], v[90:91], v[94:95]
	v_pk_fma_f32 v[34:35], v[12:13], v[88:89], v[92:93]
	v_pk_fma_f32 v[32:33], v[22:23], v[86:87], v[32:33]
	v_pk_fma_f32 v[34:35], v[20:21], v[84:85], v[34:35]
	v_pk_fma_f32 v[30:31], v[30:31], v[78:79], v[32:33]
	v_pk_fma_f32 v[28:29], v[28:29], v[76:77], v[34:35]
	v_mul_f32_e32 v34, 0xbfb8aa3b, v30
	v_mul_f32_e32 v32, 0xbfb8aa3b, v28
	v_mul_f32_e32 v33, 0xbfb8aa3b, v29
	v_mul_f32_e32 v35, 0xbfb8aa3b, v31
	v_exp_f32_e32 v32, v32
	v_exp_f32_e32 v33, v33
	v_exp_f32_e32 v34, v34
	v_exp_f32_e32 v35, v35
	v_add_f32_e32 v32, 1.0, v32
	v_add_f32_e32 v33, 1.0, v33
	v_add_f32_e32 v34, 1.0, v34
	v_add_f32_e32 v35, 1.0, v35
	v_rcp_f32_e32 v32, v32
	v_rcp_f32_e32 v33, v33
	v_rcp_f32_e32 v34, v34
	v_rcp_f32_e32 v35, v35
	v_pk_mul_f32 v[28:29], v[28:29], v[32:33]
	s_nop 0
	v_pk_mul_f32 v[24:25], v[24:25], v[28:29]
	v_pk_mul_f32 v[30:31], v[30:31], v[34:35]
	v_cvt_pk_bf16_f32 v194, v24, v25
	s_nop 0
	v_pk_mul_f32 v[26:27], v[26:27], v[30:31]
	s_nop 0
	v_cvt_pk_bf16_f32 v195, v26, v27
	v_mad_i64_i32 v[26:27], s[6:7], v217, s37, v[50:51]
	global_store_dwordx4 v[26:27], v[192:195], off nt
; __device__ __forceinline__ unsigned cvt_pk_bf16(float lo, float hi) { unsigned r; asm("v_cvt_pk_bf16_f32 %0, %1, %2" : "=v"(r) : "v"(lo), "v"(hi)); return r; }
;     __device__ __forceinline__ void operator()(const f32x4 (&acc)[2][2][4][2], const CU2& u, int wr, int wc, int fr_, int fq_) const {
;     ...
;             for (int j = 0; j < 8; ++j) {
;                 const f32x4 xg = acc[j >> 2][0][j & 3][n] * rsv[j], xv = acc[j >> 2][1][j & 3][n] * rsv[j];
;                 const f32x4 gc = gb + g2 * xg + g1 * pg1 + g0 * pg2, vc = vb + v2 * xv + v1 * pv1 + v0 * pv2;
;                 f32x4 sg;
; #pragma unroll
;                 for (int e = 0; e < 4; ++e) sg[e] = __builtin_amdgcn_rcpf(1.f + __expf(-gc[e]));
;                 const f32x4 o4 = gc * sg * vc;
;                 pg2 = pg1; pg1 = xg; pv2 = pv1; pv1 = xv;
;                 if (rb + j >= 2 && tb + j < T_) { u32x2 w; w.x = cvt_pk_bf16(o4[0], o4[1]); w.y = cvt_pk_bf16(o4[2], o4[3]); *(u32x2*)(act + (size_t)(tb + j) * FF_ + 128 * u.pn + cl + 4 * n) = w; }
.LBB0_959:
	s_or_b64 exec, exec, s[4:5]
	v_mov_b32_e32 v217, v216
	v_mov_b32_e32 v24, v216
	v_mov_b32_e32 v25, v216
	v_pk_mul_f32 v[6:7], v[6:7], v[24:25]
	v_pk_mul_f32 v[4:5], v[4:5], v[216:217]
	v_pk_mul_f32 v[2:3], v[2:3], v[24:25]
	v_pk_mul_f32 v[0:1], v[0:1], v[216:217]
	s_and_saveexec_b64 s[4:5], s[26:27]
	s_cbranch_execz .LBB0_961
	v_pk_fma_f32 v[24:25], v[2:3], v[102:103], v[106:107]
	v_pk_fma_f32 v[26:27], v[0:1], v[100:101], v[104:105]
	v_pk_fma_f32 v[24:25], v[10:11], v[98:99], v[24:25]
	v_pk_fma_f32 v[26:27], v[8:9], v[96:97], v[26:27]
	v_pk_fma_f32 v[18:19], v[18:19], v[82:83], v[24:25]
	v_pk_fma_f32 v[16:17], v[16:17], v[80:81], v[26:27]
	v_pk_fma_f32 v[24:25], v[6:7], v[90:91], v[94:95]
	v_pk_fma_f32 v[26:27], v[4:5], v[88:89], v[92:93]
	v_pk_fma_f32 v[24:25], v[14:15], v[86:87], v[24:25]
	v_pk_fma_f32 v[26:27], v[12:13], v[84:85], v[26:27]
	v_pk_fma_f32 v[22:23], v[22:23], v[78:79], v[24:25]
	v_pk_fma_f32 v[20:21], v[20:21], v[76:77], v[26:27]
	v_mul_f32_e32 v26, 0xbfb8aa3b, v22
	v_mul_f32_e32 v24, 0xbfb8aa3b, v20
	v_mul_f32_e32 v25, 0xbfb8aa3b, v21
	v_mul_f32_e32 v27, 0xbfb8aa3b, v23
	v_exp_f32_e32 v24, v24
	v_exp_f32_e32 v25, v25
	v_exp_f32_e32 v26, v26
	v_exp_f32_e32 v27, v27
	v_add_f32_e32 v24, 1.0, v24
	v_add_f32_e32 v25, 1.0, v25
	v_add_f32_e32 v26, 1.0, v26
	v_add_f32_e32 v27, 1.0, v27
	v_rcp_f32_e32 v24, v24
	v_rcp_f32_e32 v25, v25
	v_rcp_f32_e32 v26, v26
	v_rcp_f32_e32 v27, v27
	v_pk_mul_f32 v[20:21], v[20:21], v[24:25]
	s_nop 0
	v_pk_mul_f32 v[16:17], v[16:17], v[20:21]
	v_pk_mul_f32 v[22:23], v[22:23], v[26:27]
	v_cvt_pk_bf16_f32 v198, v16, v17
	s_nop 0
	v_pk_mul_f32 v[18:19], v[18:19], v[22:23]
	s_nop 0
	v_cvt_pk_bf16_f32 v199, v18, v19
	v_mad_i64_i32 v[18:19], s[6:7], v246, s37, v[50:51]
	global_store_dwordx4 v[18:19], v[196:199], off nt
.LBB0_961:
	s_or_b64 exec, exec, s[4:5]
	s_and_saveexec_b64 s[4:5], s[28:29]
	s_cbranch_execz .LBB0_963
	v_pk_fma_f32 v[16:17], v[110:111], v[102:103], v[106:107]
	v_pk_fma_f32 v[18:19], v[62:63], v[100:101], v[104:105]
	v_pk_fma_f32 v[16:17], v[2:3], v[98:99], v[16:17]
	v_pk_fma_f32 v[18:19], v[0:1], v[96:97], v[18:19]
	v_pk_fma_f32 v[10:11], v[10:11], v[82:83], v[16:17]
	v_pk_fma_f32 v[8:9], v[8:9], v[80:81], v[18:19]
	v_pk_fma_f32 v[16:17], v[64:65], v[90:91], v[94:95]
	v_pk_fma_f32 v[18:19], v[48:49], v[88:89], v[92:93]
	v_pk_fma_f32 v[16:17], v[6:7], v[86:87], v[16:17]
	v_pk_fma_f32 v[18:19], v[4:5], v[84:85], v[18:19]
	v_pk_fma_f32 v[14:15], v[14:15], v[78:79], v[16:17]
	v_pk_fma_f32 v[12:13], v[12:13], v[76:77], v[18:19]
	v_mul_f32_e32 v18, 0xbfb8aa3b, v14
	v_mul_f32_e32 v16, 0xbfb8aa3b, v12
	v_mul_f32_e32 v17, 0xbfb8aa3b, v13
	v_mul_f32_e32 v19, 0xbfb8aa3b, v15
	v_exp_f32_e32 v16, v16
	v_exp_f32_e32 v17, v17
	v_exp_f32_e32 v18, v18
	v_exp_f32_e32 v19, v19
	v_add_f32_e32 v16, 1.0, v16
	v_add_f32_e32 v17, 1.0, v17
	v_add_f32_e32 v18, 1.0, v18
	v_add_f32_e32 v19, 1.0, v19
	v_rcp_f32_e32 v16, v16
	v_rcp_f32_e32 v17, v17
	v_rcp_f32_e32 v18, v18
	v_rcp_f32_e32 v19, v19
	v_pk_mul_f32 v[12:13], v[12:13], v[16:17]
	s_nop 0
	v_pk_mul_f32 v[8:9], v[8:9], v[12:13]
	v_pk_mul_f32 v[14:15], v[14:15], v[18:19]
	v_cvt_pk_bf16_f32 v250, v8, v9
	s_nop 0
	v_pk_mul_f32 v[10:11], v[10:11], v[14:15]
	s_nop 0
	v_cvt_pk_bf16_f32 v251, v10, v11
	v_mad_i64_i32 v[10:11], s[6:7], v245, s37, v[50:51]
	global_store_dwordx4 v[10:11], v[248:251], off nt
.LBB0_963:
	s_or_b64 exec, exec, s[4:5]
	s_and_saveexec_b64 s[4:5], s[0:1]
	s_cbranch_execz .LBB0_965
	v_pk_fma_f32 v[12:13], v[52:53], v[88:89], v[92:93]
	v_pk_fma_f32 v[8:9], v[112:113], v[102:103], v[106:107]
	v_pk_fma_f32 v[12:13], v[48:49], v[84:85], v[12:13]
	v_pk_fma_f32 v[10:11], v[66:67], v[100:101], v[104:105]
	v_pk_fma_f32 v[4:5], v[4:5], v[76:77], v[12:13]
	v_pk_fma_f32 v[8:9], v[110:111], v[98:99], v[8:9]
	v_mul_f32_e32 v12, 0xbfb8aa3b, v4
	v_exp_f32_e32 v14, v12
	v_pk_fma_f32 v[12:13], v[108:109], v[90:91], v[94:95]
	v_pk_fma_f32 v[10:11], v[62:63], v[96:97], v[10:11]
	v_pk_fma_f32 v[12:13], v[64:65], v[86:87], v[12:13]
	v_pk_fma_f32 v[2:3], v[2:3], v[82:83], v[8:9]
	v_pk_fma_f32 v[6:7], v[6:7], v[78:79], v[12:13]
	v_add_f32_e32 v12, 1.0, v14
	v_mul_f32_e32 v13, 0xbfb8aa3b, v5
	v_mul_f32_e32 v14, 0xbfb8aa3b, v6
	v_mul_f32_e32 v15, 0xbfb8aa3b, v7
	v_exp_f32_e32 v13, v13
	v_exp_f32_e32 v14, v14
	v_exp_f32_e32 v15, v15
	v_rcp_f32_e32 v12, v12
	v_add_f32_e32 v13, 1.0, v13
	v_add_f32_e32 v14, 1.0, v14
	v_add_f32_e32 v15, 1.0, v15
	v_rcp_f32_e32 v14, v14
	v_rcp_f32_e32 v15, v15
	v_rcp_f32_e32 v13, v13
	v_pk_fma_f32 v[0:1], v[0:1], v[80:81], v[10:11]
	v_pk_mul_f32 v[6:7], v[6:7], v[14:15]
	v_pk_mul_f32 v[4:5], v[4:5], v[12:13]
	v_pk_mul_f32 v[2:3], v[2:3], v[6:7]
	v_pk_mul_f32 v[0:1], v[0:1], v[4:5]
	s_nop 0
	v_cvt_pk_bf16_f32 v122, v0, v1
	v_cvt_pk_bf16_f32 v123, v2, v3
	v_mad_i64_i32 v[2:3], s[0:1], v244, s37, v[50:51]
	global_store_dwordx4 v[2:3], v[120:123], off nt
